# adds census guard: XCC-rank scan unit map only when every XCC hosts 32 workgroups, else baseline map
# baseline (speedup 1.0000x reference)
.LBB0_610:
	v_readlane_b32 s0, v247, 52
	v_readlane_b32 s1, v247, 53
	s_andn2_b64 vcc, exec, s[0:1]
	s_mov_b32 s9, s55
	s_cbranch_vccnz .LBB0_612
	v_mov_b32_e32 v96, 0
	global_load_dword v97, v96, s[28:29] offset:1024 sc1
	global_load_dword v98, v96, s[28:29] offset:1280 sc1
	global_load_dword v99, v96, s[28:29] offset:1536 sc1
	global_load_dword v100, v96, s[28:29] offset:1792 sc1
	global_load_dword v101, v96, s[28:29] offset:2048 sc1
	global_load_dword v102, v96, s[28:29] offset:2304 sc1
	global_load_dword v103, v96, s[28:29] offset:2560 sc1
	global_load_dword v104, v96, s[28:29] offset:2816 sc1
	v_mov_b32_e32 v105, 0x23fd0
	ds_read_b32 v105, v105
	s_waitcnt vmcnt(0)
	v_xor_b32_e32 v97, 32, v97
	v_xor_b32_e32 v98, 32, v98
	v_xor_b32_e32 v99, 32, v99
	v_xor_b32_e32 v100, 32, v100
	v_xor_b32_e32 v101, 32, v101
	v_xor_b32_e32 v102, 32, v102
	v_xor_b32_e32 v103, 32, v103
	v_xor_b32_e32 v104, 32, v104
	v_or3_b32 v97, v97, v98, v99
	v_or3_b32 v100, v100, v101, v102
	v_or3_b32 v97, v97, v100, v103
	v_or_b32_e32 v97, v97, v104
	s_nop 0
	v_readfirstlane_b32 s0, v97
	s_waitcnt lgkmcnt(0)
	v_readfirstlane_b32 s1, v105
	s_cmp_lg_u32 s0, 0
	s_cbranch_scc1 .Lscan_map_orig
	v_readlane_b32 s0, v247, 7
	s_lshl_b32 s0, s0, 5
	s_add_i32 s9, s0, s1
	s_branch .LBB0_612
.Lscan_map_orig:
	s_lshl_b32 s0, s55, 3
	s_and_b32 s0, s0, 56
	s_ashr_i32 s1, s55, 5
	s_add_i32 s0, s0, s1
	s_lshl_b32 s0, s0, 2
	s_bfe_u32 s1, s55, 0x20003
	s_or_b32 s9, s0, s1
